# attention loops: m0 write moved ahead of the scalar address add so the s_nop before each LDS-DMA goes; pad before the tile-sum add removed
# speedup vs baseline: 1.0030x; 1.0030x over previous
.LBB0_168:
	s_barrier
	s_cmp_lt_u32 s22, s19
	s_mov_b64 s[26:27], -1
	s_cbranch_scc1 .LBB0_174
	s_add_i32 s22, s23, 2
	s_cmp_ge_u32 s22, s17
	s_cbranch_scc1 .LBB0_171
	s_lshl_b32 s26, s48, 14
	s_add_i32 s26, s11, s26
	s_add_i32 s27, s26, 0x2000
	s_mov_b32 m0, s26
	s_add_u32 s100, s8, s80
	s_addc_u32 s101, s9, s81
	global_load_lds_dwordx4 v214, s[100:101]
	s_mov_b32 m0, s27
	s_add_u32 s100, s8, s62
	s_addc_u32 s101, s9, s63
	global_load_lds_dwordx4 v214, s[100:101]
.LBB0_171:
	s_andn2_b64 vcc, exec, s[88:89]
	s_cbranch_vccnz .LBB0_173
	s_lshl_b32 s26, s31, 14
	s_add_i32 s26, s11, s26
	s_add_u32 s100, s8, s96
	s_addc_u32 s101, s9, s97
	s_add_i32 m0, s26, 0xc000
	s_add_i32 s26, s26, 0xe000
	global_load_lds_dwordx4 v216, s[100:101]
	s_mov_b32 m0, s26
	s_add_u32 s100, s8, s58
	s_addc_u32 s101, s9, s59
	global_load_lds_dwordx4 v216, s[100:101]

.LBB0_174:
	s_and_b64 vcc, exec, s[26:27]
	s_cbranch_vccz .LBB0_200
	s_lshl_b32 s22, s49, 14
	s_add_i32 s54, s22, 0
	s_mov_b64 s[26:27], -1
	s_cmp_ge_u32 s23, s19
	v_add_u32_e32 v249, s54, v244
	v_add_u32_e32 v212, s54, v245
	s_cbranch_scc0 .LBB0_185
	ds_read_b128 v[98:101], v249 offset:49152
	ds_read_b128 v[114:117], v249 offset:53248
	ds_read_b128 v[130:133], v249 offset:57344
	ds_read_b128 v[194:197], v249 offset:61440
	s_waitcnt lgkmcnt(0)
	v_mfma_f32_32x32x16_bf16 v[82:97], v[98:101], v[162:165], v[34:49]
	ds_read_b128 v[206:209], v212 offset:49152
	v_mfma_f32_32x32x16_bf16 v[98:113], v[114:117], v[162:165], v[50:65]
	ds_read_b128 v[198:201], v212 offset:53248
	s_add_i32 s22, s23, 2
	s_cmp_lt_u32 s22, s17
	s_cselect_b64 s[26:27], -1, 0
	s_cmp_ge_u32 s22, s17
	s_cbranch_scc1 .LBB0_178
	s_lshl_b32 s40, s48, 14
	s_add_i32 m0, s11, s40
	s_add_u32 s100, s8, s80
	s_addc_u32 s101, s9, s81
	global_load_lds_dwordx4 v214, s[100:101]
.LBB0_178:
	v_mfma_f32_32x32x16_bf16 v[114:129], v[130:133], v[162:165], v[18:33]
	ds_read_b128 v[202:205], v212 offset:57344
	v_mfma_f32_32x32x16_bf16 v[130:145], v[194:197], v[162:165], v[2:17]
	ds_read_b128 v[194:197], v212 offset:61440
	s_waitcnt lgkmcnt(0)
	v_mfma_f32_32x32x16_bf16 v[82:97], v[206:209], v[170:173], v[82:97]
	v_add_u32_e32 v250, s54, v246
	ds_read_b128 v[206:209], v250 offset:49152
	v_mfma_f32_32x32x16_bf16 v[98:113], v[198:201], v[170:173], v[98:113]
	ds_read_b128 v[198:201], v250 offset:53248
	s_andn2_b64 vcc, exec, s[26:27]
	s_cbranch_vccnz .LBB0_180
	s_lshl_b32 s26, s48, 14
	s_add_i32 s26, s11, s26
	s_add_i32 m0, s26, 0x2000
	s_add_u32 s100, s8, s62
	s_addc_u32 s101, s9, s63
	global_load_lds_dwordx4 v214, s[100:101]
.LBB0_180:
	v_mfma_f32_32x32x16_bf16 v[114:129], v[202:205], v[170:173], v[114:129]
	ds_read_b128 v[202:205], v250 offset:57344
	v_mfma_f32_32x32x16_bf16 v[130:145], v[194:197], v[170:173], v[130:145]
	ds_read_b128 v[194:197], v250 offset:61440
	s_waitcnt lgkmcnt(0)
	v_mfma_f32_32x32x16_bf16 v[82:97], v[206:209], v[178:181], v[82:97]
	v_add_u32_e32 v250, s54, v247
	ds_read_b128 v[206:209], v250 offset:49152
	v_mfma_f32_32x32x16_bf16 v[98:113], v[198:201], v[178:181], v[98:113]
	ds_read_b128 v[198:201], v250 offset:53248
	v_cndmask_b32_e64 v224, 0, 1, s[88:89]
	v_cmp_ne_u32_e64 s[40:41], 1, v224
	s_andn2_b64 vcc, exec, s[88:89]
	s_cbranch_vccnz .LBB0_182
	s_lshl_b32 s26, s31, 14
	s_add_i32 s26, s11, s26
	s_add_i32 m0, s26, 0xc000
	s_add_u32 s100, s8, s96
	s_addc_u32 s101, s9, s97
	global_load_lds_dwordx4 v216, s[100:101]
.LBB0_182:
	v_mfma_f32_32x32x16_bf16 v[114:129], v[202:205], v[178:181], v[114:129]
	ds_read_b128 v[202:205], v250 offset:57344
	v_mfma_f32_32x32x16_bf16 v[130:145], v[194:197], v[178:181], v[130:145]
	ds_read_b128 v[194:197], v250 offset:61440
	s_waitcnt lgkmcnt(0)
	v_mfma_f32_32x32x16_bf16 v[82:97], v[206:209], v[186:189], v[82:97]
	v_mfma_f32_32x32x16_bf16 v[98:113], v[198:201], v[186:189], v[98:113]
	s_and_b64 vcc, exec, s[40:41]
	s_cbranch_vccnz .LBB0_184
	s_lshl_b32 s26, s31, 14
	s_add_i32 s26, s11, s26
	s_add_i32 m0, s26, 0xe000
	s_add_u32 s100, s8, s58
	s_addc_u32 s101, s9, s59
	global_load_lds_dwordx4 v216, s[100:101]

.LBB0_188:
	s_waitcnt lgkmcnt(0)
	v_mfma_f32_32x32x16_bf16 v[34:49], v[126:129], v[162:165], v[34:49]
	ds_read_b128 v[126:129], v212 offset:49152
	s_nop 0
	v_exp_f32_e32 v130, v82
	v_exp_f32_e32 v131, v83
	v_add_f32_e32 v132, v1, v130
	v_add_f32_e32 v133, v1, v131
	v_cvt_pk_bf16_f32 v166, v130, v131
	v_mfma_f32_32x32x16_bf16 v[50:65], v[122:125], v[162:165], v[50:65]
	ds_read_b128 v[122:125], v212 offset:53248
	v_exp_f32_e32 v134, v84
	v_exp_f32_e32 v135, v85
	s_add_i32 s22, s23, 2
	s_cmp_lt_u32 s22, s17
	v_add_f32_e32 v130, v132, v134
	v_add_f32_e32 v131, v133, v135
	v_cvt_pk_bf16_f32 v167, v134, v135
	s_cselect_b64 s[26:27], -1, 0
	s_cmp_ge_u32 s22, s17
	s_cbranch_scc1 .LBB0_190
	s_lshl_b32 s40, s48, 14
	s_add_i32 m0, s11, s40
	s_add_u32 s100, s8, s80
	s_addc_u32 s101, s9, s81
	global_load_lds_dwordx4 v214, s[100:101]
.LBB0_190:
	v_mfma_f32_32x32x16_bf16 v[18:33], v[118:121], v[162:165], v[18:33]
	ds_read_b128 v[118:121], v212 offset:57344
	v_exp_f32_e32 v132, v86
	v_exp_f32_e32 v133, v87
	v_add_f32_e32 v130, v130, v132
	v_add_f32_e32 v131, v131, v133
	v_cvt_pk_bf16_f32 v168, v132, v133
	v_mfma_f32_32x32x16_bf16 v[2:17], v[114:117], v[162:165], v[2:17]
	ds_read_b128 v[114:117], v212 offset:61440
	v_exp_f32_e32 v132, v88
	v_exp_f32_e32 v133, v89
	v_add_f32_e32 v134, v130, v132
	v_add_f32_e32 v131, v131, v133
	v_cvt_pk_bf16_f32 v169, v132, v133
	s_waitcnt lgkmcnt(0)
	v_mfma_f32_32x32x16_bf16 v[34:49], v[126:129], v[170:173], v[34:49]
	v_add_u32_e32 v130, s54, v246
	ds_read_b128 v[126:129], v130 offset:49152
	v_exp_f32_e32 v132, v90
	v_exp_f32_e32 v133, v91
	v_add_f32_e32 v134, v134, v132
	v_add_f32_e32 v135, v131, v133
	v_cvt_pk_bf16_f32 v174, v132, v133
	v_mfma_f32_32x32x16_bf16 v[50:65], v[122:125], v[170:173], v[50:65]
	ds_read_b128 v[122:125], v130 offset:53248
	v_exp_f32_e32 v133, v92
	v_exp_f32_e32 v136, v93
	v_add_f32_e32 v131, v134, v133
	v_add_f32_e32 v132, v135, v136
	s_andn2_b64 vcc, exec, s[26:27]
	v_cvt_pk_bf16_f32 v175, v133, v136
	s_cbranch_vccnz .LBB0_192
	s_lshl_b32 s26, s48, 14
	s_add_i32 s26, s11, s26
	s_add_i32 m0, s26, 0x2000
	s_add_u32 s100, s8, s62
	s_addc_u32 s101, s9, s63
	global_load_lds_dwordx4 v214, s[100:101]
.LBB0_192:
	v_mfma_f32_32x32x16_bf16 v[18:33], v[118:121], v[170:173], v[18:33]
	ds_read_b128 v[118:121], v130 offset:57344
	v_exp_f32_e32 v133, v94
	v_exp_f32_e32 v134, v95
	v_add_f32_e32 v131, v131, v133
	v_add_f32_e32 v132, v132, v134
	v_cvt_pk_bf16_f32 v176, v133, v134
	v_mfma_f32_32x32x16_bf16 v[2:17], v[114:117], v[170:173], v[2:17]
	ds_read_b128 v[114:117], v130 offset:61440
	v_exp_f32_e32 v130, v96
	v_exp_f32_e32 v133, v97
	v_add_f32_e32 v131, v131, v130
	v_add_f32_e32 v132, v132, v133
	v_cvt_pk_bf16_f32 v177, v130, v133
	s_waitcnt lgkmcnt(0)
	v_mfma_f32_32x32x16_bf16 v[34:49], v[126:129], v[178:181], v[34:49]
	v_add_u32_e32 v130, s54, v247
	ds_read_b128 v[126:129], v130 offset:49152
	v_exp_f32_e32 v133, v98
	v_exp_f32_e32 v134, v99
	v_add_f32_e32 v131, v131, v133
	v_add_f32_e32 v132, v132, v134
	v_cvt_pk_bf16_f32 v182, v133, v134
	v_mfma_f32_32x32x16_bf16 v[50:65], v[122:125], v[178:181], v[50:65]
	v_exp_f32_e32 v133, v100
	v_exp_f32_e32 v134, v101
	ds_read_b128 v[122:125], v130 offset:53248
	v_add_f32_e32 v131, v131, v133
	v_add_f32_e32 v132, v132, v134
	v_cvt_pk_bf16_f32 v183, v133, v134
	v_cndmask_b32_e64 v133, 0, 1, s[88:89]
	v_cmp_ne_u32_e64 s[40:41], 1, v133
	s_andn2_b64 vcc, exec, s[88:89]
	s_cbranch_vccnz .LBB0_194
	s_lshl_b32 s26, s31, 14
	s_add_i32 s26, s11, s26
	s_add_i32 m0, s26, 0xc000
	s_add_u32 s100, s8, s96
	s_addc_u32 s101, s9, s97
	global_load_lds_dwordx4 v216, s[100:101]
.LBB0_194:
	v_mfma_f32_32x32x16_bf16 v[18:33], v[118:121], v[178:181], v[18:33]
	ds_read_b128 v[118:121], v130 offset:57344
	v_exp_f32_e32 v133, v102
	v_exp_f32_e32 v134, v103
	v_add_f32_e32 v131, v131, v133
	v_add_f32_e32 v132, v132, v134
	v_cvt_pk_bf16_f32 v184, v133, v134
	v_mfma_f32_32x32x16_bf16 v[2:17], v[114:117], v[178:181], v[2:17]
	ds_read_b128 v[114:117], v130 offset:61440
	v_exp_f32_e32 v130, v104
	v_exp_f32_e32 v133, v105
	v_add_f32_e32 v131, v131, v130
	v_add_f32_e32 v132, v132, v133
	v_cvt_pk_bf16_f32 v185, v130, v133
	s_waitcnt lgkmcnt(0)
	v_mfma_f32_32x32x16_bf16 v[34:49], v[126:129], v[186:189], v[34:49]
	v_exp_f32_e32 v126, v106
	v_exp_f32_e32 v127, v107
	v_add_f32_e32 v128, v131, v126
	v_add_f32_e32 v129, v132, v127
	v_cvt_pk_bf16_f32 v190, v126, v127
	v_mfma_f32_32x32x16_bf16 v[50:65], v[122:125], v[186:189], v[50:65]
	v_exp_f32_e32 v124, v108
	v_exp_f32_e32 v125, v109
	v_add_f32_e32 v122, v128, v124
	v_add_f32_e32 v123, v129, v125
	s_and_b64 vcc, exec, s[40:41]
	v_cvt_pk_bf16_f32 v191, v124, v125
	s_cbranch_vccnz .LBB0_196
	s_lshl_b32 s26, s31, 14
	s_add_i32 s26, s11, s26
	s_add_i32 m0, s26, 0xe000
	s_add_u32 s100, s8, s58
	s_addc_u32 s101, s9, s59
	global_load_lds_dwordx4 v216, s[100:101]
.LBB0_196:
	v_mfma_f32_32x32x16_bf16 v[18:33], v[118:121], v[186:189], v[18:33]
	v_exp_f32_e32 v118, v110
	v_exp_f32_e32 v119, v111
	v_add_f32_e32 v120, v122, v118
	v_add_f32_e32 v121, v123, v119
	v_cvt_pk_bf16_f32 v192, v118, v119
	v_mfma_f32_32x32x16_bf16 v[2:17], v[114:117], v[186:189], v[2:17]
	v_exp_f32_e32 v114, v112
	v_exp_f32_e32 v115, v113
	v_add_f32_e32 v116, v120, v114
	v_add_f32_e32 v117, v121, v115
	v_cvt_pk_bf16_f32 v193, v114, v115
	v_add_f32_e32 v212, v116, v117
	v_cmp_nge_f32_e32 vcc, s7, v212
	s_cbranch_vccz .LBB0_198
	v_max_f32_e32 v66, v99, v99
	v_max_f32_e32 v67, v83, v83
	v_max_f32_e32 v66, v67, v66
	v_max3_f32 v66, v82, v98, v66
	v_max3_f32 v67, v100, v85, v101
	v_max3_f32 v66, v66, v84, v67
	v_max3_f32 v67, v102, v87, v103
	v_max3_f32 v66, v66, v86, v67
	v_max3_f32 v67, v104, v89, v105
	v_max3_f32 v66, v66, v88, v67
	v_max3_f32 v67, v106, v91, v107
	v_max3_f32 v66, v66, v90, v67
	v_max3_f32 v67, v108, v93, v109
	v_max3_f32 v66, v66, v92, v67
	v_max3_f32 v67, v110, v95, v111
	v_max3_f32 v66, v66, v94, v67
	v_max3_f32 v67, v112, v97, v113
	v_max3_f32 v66, v66, v96, v67
	v_mov_b32_e32 v67, v66
	s_nop 1
	v_permlane32_swap_b32_e32 v66, v67
	v_max_f32_e32 v67, v67, v67
	v_max_f32_e32 v66, v66, v66
	v_max_f32_e32 v66, v66, v67
	v_cmp_lt_f32_e32 vcc, s57, v66
	s_nop 1
	v_cndmask_b32_e32 v68, 0, v66, vcc
	v_sub_f32_e32 v66, v82, v68
	v_exp_f32_e32 v116, v66
	v_sub_f32_e32 v66, v98, v68
	v_exp_f32_e32 v117, v66
	v_sub_f32_e32 v66, v83, v68
	v_exp_f32_e32 v118, v66
	v_sub_f32_e32 v66, v99, v68
	v_exp_f32_e32 v119, v66
	v_sub_f32_e32 v66, v84, v68
	v_exp_f32_e32 v98, v66
	v_sub_f32_e32 v66, v100, v68
	v_exp_f32_e32 v82, v66
	v_add_f32_e32 v66, v117, v116
	v_add_f32_e32 v99, 0, v66
	v_add_f32_e32 v83, v119, v118
	v_pk_add_f32 v[66:67], v[82:83], v[98:99]
	v_cvt_pk_bf16_f32 v166, v116, v118
	v_pk_add_f32 v[114:115], v[66:67], v[66:67] op_sel_hi:[0,1]
	v_sub_f32_e32 v66, v85, v68
	v_exp_f32_e32 v83, v66
	v_sub_f32_e32 v66, v101, v68
	v_exp_f32_e32 v99, v66
	v_sub_f32_e32 v66, v86, v68
	v_exp_f32_e32 v114, v66
	v_sub_f32_e32 v66, v102, v68
	v_exp_f32_e32 v84, v66
	v_add_f32_e32 v85, v99, v83
	v_cvt_pk_bf16_f32 v167, v98, v83
	v_cvt_pk_bf16_f32 v182, v117, v119
	v_pk_add_f32 v[66:67], v[84:85], v[114:115]
	v_cvt_pk_bf16_f32 v183, v82, v99
	v_pk_add_f32 v[100:101], v[66:67], v[66:67] op_sel_hi:[0,1]
	v_sub_f32_e32 v66, v87, v68
	v_exp_f32_e32 v85, v66
	v_sub_f32_e32 v66, v103, v68
	v_exp_f32_e32 v115, v66
	v_sub_f32_e32 v66, v88, v68
	v_exp_f32_e32 v100, v66
	v_sub_f32_e32 v66, v104, v68
	v_exp_f32_e32 v86, v66
	v_add_f32_e32 v87, v115, v85
	v_cvt_pk_bf16_f32 v168, v114, v85
	v_cvt_pk_bf16_f32 v184, v84, v115
	v_pk_add_f32 v[66:67], v[86:87], v[100:101]
	s_nop 0
	v_pk_add_f32 v[102:103], v[66:67], v[66:67] op_sel_hi:[0,1]
	v_sub_f32_e32 v66, v89, v68
	v_exp_f32_e32 v87, v66
	v_sub_f32_e32 v66, v105, v68
	v_exp_f32_e32 v101, v66
	v_sub_f32_e32 v66, v90, v68
	v_exp_f32_e32 v102, v66
	v_sub_f32_e32 v66, v106, v68
	v_exp_f32_e32 v88, v66
	v_add_f32_e32 v89, v101, v87
	v_cvt_pk_bf16_f32 v169, v100, v87
	v_cvt_pk_bf16_f32 v185, v86, v101
	v_pk_add_f32 v[66:67], v[88:89], v[102:103]
	s_nop 0
	v_pk_add_f32 v[104:105], v[66:67], v[66:67] op_sel_hi:[0,1]
	v_sub_f32_e32 v66, v91, v68
	v_exp_f32_e32 v89, v66
	v_sub_f32_e32 v66, v107, v68
	v_exp_f32_e32 v103, v66
	v_sub_f32_e32 v66, v92, v68
	v_exp_f32_e32 v104, v66
	v_sub_f32_e32 v66, v108, v68
	v_exp_f32_e32 v90, v66
	v_sub_f32_e32 v66, v97, v68
	v_add_f32_e32 v91, v103, v89
	v_exp_f32_e32 v97, v66
	v_pk_add_f32 v[66:67], v[90:91], v[104:105]
	v_cvt_pk_bf16_f32 v174, v102, v89
	v_pk_add_f32 v[106:107], v[66:67], v[66:67] op_sel_hi:[0,1]
	v_sub_f32_e32 v66, v93, v68
	v_exp_f32_e32 v91, v66
	v_sub_f32_e32 v66, v109, v68
	v_exp_f32_e32 v105, v66
	v_sub_f32_e32 v66, v94, v68
	v_exp_f32_e32 v106, v66
	v_sub_f32_e32 v66, v110, v68
	v_exp_f32_e32 v92, v66
	v_sub_f32_e32 v66, v113, v68
	v_add_f32_e32 v93, v105, v91
	v_exp_f32_e32 v110, v66
	v_pk_add_f32 v[66:67], v[92:93], v[106:107]
	v_cvt_pk_bf16_f32 v175, v104, v91
	v_pk_add_f32 v[108:109], v[66:67], v[66:67] op_sel_hi:[0,1]
	v_sub_f32_e32 v66, v95, v68
	v_exp_f32_e32 v93, v66
	v_sub_f32_e32 v66, v111, v68
	v_exp_f32_e32 v107, v66
	v_sub_f32_e32 v66, v96, v68
	v_exp_f32_e32 v108, v66
	v_sub_f32_e32 v66, v112, v68
	v_exp_f32_e32 v94, v66
	v_add_f32_e32 v95, v107, v93
	v_exp_f32_e64 v96, -v68
	v_add_f32_e32 v212, v110, v97
	v_pk_add_f32 v[66:67], v[94:95], v[108:109]
	v_cvt_pk_bf16_f32 v176, v106, v93
	v_pk_add_f32 v[66:67], v[66:67], v[66:67] op_sel:[0,1] op_sel_hi:[1,0]
	v_pk_mul_f32 v[48:49], v[48:49], v[96:97] op_sel_hi:[1,0]
	v_mov_b32_e32 v67, v68
	v_pk_add_f32 v[212:213], v[212:213], v[66:67]
	v_pk_mul_f32 v[46:47], v[46:47], v[96:97] op_sel_hi:[1,0]
	v_xor_b32_e32 v66, 0x80000000, v213
	v_mov_b32_e32 v67, v66
	v_mov_b32_e32 v68, v66
	v_mov_b32_e32 v69, v66
	v_mov_b32_e32 v70, v66
	v_mov_b32_e32 v71, v66
	v_mov_b32_e32 v72, v66
	v_mov_b32_e32 v73, v66
	v_mov_b32_e32 v74, v66
	v_mov_b32_e32 v75, v66
	v_mov_b32_e32 v76, v66
	v_mov_b32_e32 v77, v66
	v_mov_b32_e32 v78, v66
	v_mov_b32_e32 v79, v66
	v_mov_b32_e32 v80, v66
	v_mov_b32_e32 v81, v66
	v_pk_mul_f32 v[44:45], v[44:45], v[96:97] op_sel_hi:[1,0]
	v_pk_mul_f32 v[42:43], v[42:43], v[96:97] op_sel_hi:[1,0]
	v_pk_mul_f32 v[40:41], v[40:41], v[96:97] op_sel_hi:[1,0]
	v_pk_mul_f32 v[38:39], v[38:39], v[96:97] op_sel_hi:[1,0]
	v_pk_mul_f32 v[36:37], v[36:37], v[96:97] op_sel_hi:[1,0]
	v_pk_mul_f32 v[34:35], v[34:35], v[96:97] op_sel_hi:[1,0]
	v_pk_mul_f32 v[64:65], v[64:65], v[96:97] op_sel_hi:[1,0]
	v_pk_mul_f32 v[62:63], v[62:63], v[96:97] op_sel_hi:[1,0]
	v_pk_mul_f32 v[60:61], v[60:61], v[96:97] op_sel_hi:[1,0]
	v_pk_mul_f32 v[58:59], v[58:59], v[96:97] op_sel_hi:[1,0]
	v_pk_mul_f32 v[56:57], v[56:57], v[96:97] op_sel_hi:[1,0]
	v_pk_mul_f32 v[54:55], v[54:55], v[96:97] op_sel_hi:[1,0]
	v_pk_mul_f32 v[52:53], v[52:53], v[96:97] op_sel_hi:[1,0]
	v_pk_mul_f32 v[50:51], v[50:51], v[96:97] op_sel_hi:[1,0]
	v_pk_mul_f32 v[32:33], v[32:33], v[96:97] op_sel_hi:[1,0]
	v_pk_mul_f32 v[30:31], v[30:31], v[96:97] op_sel_hi:[1,0]
	v_pk_mul_f32 v[28:29], v[28:29], v[96:97] op_sel_hi:[1,0]
	v_pk_mul_f32 v[26:27], v[26:27], v[96:97] op_sel_hi:[1,0]
	v_pk_mul_f32 v[24:25], v[24:25], v[96:97] op_sel_hi:[1,0]
	v_pk_mul_f32 v[22:23], v[22:23], v[96:97] op_sel_hi:[1,0]
	v_pk_mul_f32 v[20:21], v[20:21], v[96:97] op_sel_hi:[1,0]
	v_pk_mul_f32 v[18:19], v[18:19], v[96:97] op_sel_hi:[1,0]
	v_pk_mul_f32 v[16:17], v[16:17], v[96:97] op_sel_hi:[1,0]
	v_pk_mul_f32 v[14:15], v[14:15], v[96:97] op_sel_hi:[1,0]
	v_pk_mul_f32 v[12:13], v[12:13], v[96:97] op_sel_hi:[1,0]
	v_pk_mul_f32 v[10:11], v[10:11], v[96:97] op_sel_hi:[1,0]
	v_pk_mul_f32 v[8:9], v[8:9], v[96:97] op_sel_hi:[1,0]
	v_pk_mul_f32 v[6:7], v[6:7], v[96:97] op_sel_hi:[1,0]
	v_pk_mul_f32 v[4:5], v[4:5], v[96:97] op_sel_hi:[1,0]
	v_pk_mul_f32 v[2:3], v[2:3], v[96:97] op_sel_hi:[1,0]
	v_mul_f32_e32 v242, v242, v96
	v_cvt_pk_bf16_f32 v177, v108, v97
	v_cvt_pk_bf16_f32 v190, v88, v103
	v_cvt_pk_bf16_f32 v191, v90, v105
	v_cvt_pk_bf16_f32 v192, v92, v107
	v_cvt_pk_bf16_f32 v193, v94, v110

.LBB0_208:
	s_add_i32 s26, s33, 1
	s_cmp_lg_u32 s33, 2
	s_cselect_b32 s33, s26, 0
	s_add_i32 s26, s48, 1
	s_cmp_lg_u32 s48, 2
	s_cselect_b32 s48, s26, 0
	s_add_i32 s26, s49, 1
	s_cmp_lg_u32 s49, 2
	s_cselect_b32 s49, s26, 0
	s_add_i32 s26, s31, 1
	s_barrier
	s_cmp_lg_u32 s31, 2
	s_cselect_b32 s31, s26, 0
	s_cmp_lt_u32 s23, s19
	s_mov_b64 s[26:27], -1
	s_cbranch_scc1 .LBB0_214
	s_add_i32 s26, s23, 3
	s_cmp_gt_u32 s26, s16
	s_cbranch_scc1 .LBB0_211
	s_lshl_b32 s26, s48, 14
	s_add_i32 s26, s11, s26
	s_add_i32 s27, s26, 0x2000
	s_mov_b32 m0, s26
	s_add_u32 s100, s8, s50
	s_addc_u32 s101, s9, s51
	global_load_lds_dwordx4 v214, s[100:101]
	s_mov_b32 m0, s27
	s_add_u32 s100, s8, s4
	s_addc_u32 s101, s9, s5
	global_load_lds_dwordx4 v214, s[100:101]
.LBB0_211:
	s_andn2_b64 vcc, exec, s[88:89]
	s_cbranch_vccnz .LBB0_213
	s_lshl_b32 s26, s31, 14
	s_add_i32 s26, s11, s26
	s_add_u32 s100, s8, s0
	s_addc_u32 s101, s9, s1
	s_add_i32 m0, s26, 0xc000
	s_add_i32 s26, s26, 0xe000
	global_load_lds_dwordx4 v216, s[100:101]
	s_mov_b32 m0, s26
	s_add_u32 s100, s8, s52
	s_addc_u32 s101, s9, s53
	global_load_lds_dwordx4 v216, s[100:101]

.LBB0_214:
	s_and_b64 vcc, exec, s[26:27]
	s_cbranch_vccz .LBB0_240
	s_lshl_b32 s26, s49, 14
	s_add_i32 s40, s23, 1
	s_add_i32 s54, s26, 0
	s_mov_b64 s[26:27], -1
	s_cmp_ge_u32 s40, s19
	v_add_u32_e32 v249, s54, v244
	v_add_u32_e32 v212, s54, v245
	s_cbranch_scc0 .LBB0_225
	ds_read_b128 v[98:101], v249 offset:49152
	ds_read_b128 v[114:117], v249 offset:53248
	ds_read_b128 v[130:133], v249 offset:57344
	ds_read_b128 v[194:197], v249 offset:61440
	s_waitcnt lgkmcnt(0)
	v_mfma_f32_32x32x16_bf16 v[82:97], v[98:101], v[166:169], v[34:49]
	ds_read_b128 v[206:209], v212 offset:49152
	v_mfma_f32_32x32x16_bf16 v[98:113], v[114:117], v[166:169], v[50:65]
	ds_read_b128 v[198:201], v212 offset:53248
	s_add_i32 s40, s23, 3
	s_cmp_le_u32 s40, s16
	s_cselect_b64 s[26:27], -1, 0
	s_cmp_gt_u32 s40, s16
	s_cbranch_scc1 .LBB0_218
	s_lshl_b32 s40, s48, 14
	s_add_i32 m0, s11, s40
	s_add_u32 s100, s8, s50
	s_addc_u32 s101, s9, s51
	global_load_lds_dwordx4 v214, s[100:101]
.LBB0_218:
	v_mfma_f32_32x32x16_bf16 v[114:129], v[130:133], v[166:169], v[18:33]
	ds_read_b128 v[202:205], v212 offset:57344
	v_mfma_f32_32x32x16_bf16 v[130:145], v[194:197], v[166:169], v[2:17]
	ds_read_b128 v[194:197], v212 offset:61440
	s_waitcnt lgkmcnt(0)
	v_mfma_f32_32x32x16_bf16 v[82:97], v[206:209], v[174:177], v[82:97]
	v_add_u32_e32 v250, s54, v246
	ds_read_b128 v[206:209], v250 offset:49152
	v_mfma_f32_32x32x16_bf16 v[98:113], v[198:201], v[174:177], v[98:113]
	ds_read_b128 v[198:201], v250 offset:53248
	s_andn2_b64 vcc, exec, s[26:27]
	s_cbranch_vccnz .LBB0_220
	s_lshl_b32 s26, s48, 14
	s_add_i32 s26, s11, s26
	s_add_i32 m0, s26, 0x2000
	s_add_u32 s100, s8, s4
	s_addc_u32 s101, s9, s5
	global_load_lds_dwordx4 v214, s[100:101]
.LBB0_220:
	v_mfma_f32_32x32x16_bf16 v[114:129], v[202:205], v[174:177], v[114:129]
	ds_read_b128 v[202:205], v250 offset:57344
	v_mfma_f32_32x32x16_bf16 v[130:145], v[194:197], v[174:177], v[130:145]
	ds_read_b128 v[194:197], v250 offset:61440
	s_waitcnt lgkmcnt(0)
	v_mfma_f32_32x32x16_bf16 v[82:97], v[206:209], v[182:185], v[82:97]
	v_add_u32_e32 v250, s54, v247
	ds_read_b128 v[206:209], v250 offset:49152
	v_mfma_f32_32x32x16_bf16 v[98:113], v[198:201], v[182:185], v[98:113]
	ds_read_b128 v[198:201], v250 offset:53248
	v_cndmask_b32_e64 v224, 0, 1, s[88:89]
	v_cmp_ne_u32_e64 s[40:41], 1, v224
	s_andn2_b64 vcc, exec, s[88:89]
	s_cbranch_vccnz .LBB0_222
	s_lshl_b32 s26, s31, 14
	s_add_i32 s26, s11, s26
	s_add_i32 m0, s26, 0xc000
	s_add_u32 s100, s8, s0
	s_addc_u32 s101, s9, s1
	global_load_lds_dwordx4 v216, s[100:101]
.LBB0_222:
	v_mfma_f32_32x32x16_bf16 v[114:129], v[202:205], v[182:185], v[114:129]
	ds_read_b128 v[202:205], v250 offset:57344
	v_mfma_f32_32x32x16_bf16 v[130:145], v[194:197], v[182:185], v[130:145]
	ds_read_b128 v[194:197], v250 offset:61440
	s_waitcnt lgkmcnt(0)
	v_mfma_f32_32x32x16_bf16 v[82:97], v[206:209], v[190:193], v[82:97]
	v_mfma_f32_32x32x16_bf16 v[98:113], v[198:201], v[190:193], v[98:113]
	s_and_b64 vcc, exec, s[40:41]
	s_cbranch_vccnz .LBB0_224
	s_lshl_b32 s26, s31, 14
	s_add_i32 s26, s11, s26
	s_add_i32 m0, s26, 0xe000
	s_add_u32 s100, s8, s52
	s_addc_u32 s101, s9, s53
	global_load_lds_dwordx4 v216, s[100:101]

.LBB0_232:
	v_mfma_f32_32x32x16_bf16 v[18:33], v[118:121], v[174:177], v[18:33]
	ds_read_b128 v[118:121], v132 offset:57344
	v_exp_f32_e32 v130, v94
	v_exp_f32_e32 v131, v95
	v_add_f32_e32 v133, v133, v130
	v_add_f32_e32 v134, v134, v131
	v_cvt_pk_bf16_f32 v172, v130, v131
	v_mfma_f32_32x32x16_bf16 v[2:17], v[114:117], v[174:177], v[2:17]
	ds_read_b128 v[114:117], v132 offset:61440
	v_exp_f32_e32 v130, v96
	v_exp_f32_e32 v131, v97
	v_add_f32_e32 v133, v133, v130
	v_add_f32_e32 v134, v134, v131
	v_cvt_pk_bf16_f32 v173, v130, v131
	s_waitcnt lgkmcnt(0)
	v_mfma_f32_32x32x16_bf16 v[34:49], v[126:129], v[182:185], v[34:49]
	v_add_u32_e32 v132, s54, v247
	ds_read_b128 v[126:129], v132 offset:49152
	v_exp_f32_e32 v130, v98
	v_exp_f32_e32 v131, v99
	v_add_f32_e32 v133, v133, v130
	v_add_f32_e32 v134, v134, v131
	v_cvt_pk_bf16_f32 v178, v130, v131
	v_mfma_f32_32x32x16_bf16 v[50:65], v[122:125], v[182:185], v[50:65]
	v_exp_f32_e32 v130, v100
	v_exp_f32_e32 v131, v101
	ds_read_b128 v[122:125], v132 offset:53248
	v_add_f32_e32 v133, v133, v130
	v_add_f32_e32 v134, v134, v131
	v_cvt_pk_bf16_f32 v179, v130, v131
	v_cndmask_b32_e64 v130, 0, 1, s[88:89]
	v_cmp_ne_u32_e64 s[40:41], 1, v130
	s_andn2_b64 vcc, exec, s[88:89]
	v_lshl_add_u64 v[130:131], s[8:9], 0, v[216:217]
	s_cbranch_vccnz .LBB0_234
	s_lshl_b32 s23, s31, 14
	s_add_i32 s23, s11, s23
	s_add_i32 m0, s23, 0xc000
	s_add_u32 s100, s8, s0
	s_addc_u32 s101, s9, s1
	global_load_lds_dwordx4 v216, s[100:101]

.LBB0_236:
	v_mfma_f32_32x32x16_bf16 v[18:33], v[118:121], v[190:193], v[18:33]
	v_exp_f32_e32 v118, v110
	v_exp_f32_e32 v119, v111
	v_add_f32_e32 v120, v122, v118
	v_add_f32_e32 v121, v123, v119
	v_cvt_pk_bf16_f32 v188, v118, v119
	v_mfma_f32_32x32x16_bf16 v[2:17], v[114:117], v[190:193], v[2:17]
	v_exp_f32_e32 v114, v112
	v_exp_f32_e32 v115, v113
	v_add_f32_e32 v116, v120, v114
	v_add_f32_e32 v117, v121, v115
	v_cvt_pk_bf16_f32 v189, v114, v115
	v_add_f32_e32 v212, v116, v117
	v_cmp_nge_f32_e32 vcc, s7, v212
	s_cbranch_vccz .LBB0_238
	v_max_f32_e32 v66, v99, v99
	v_max_f32_e32 v67, v83, v83
	v_max_f32_e32 v66, v67, v66
	v_max3_f32 v66, v82, v98, v66
	v_max3_f32 v67, v100, v85, v101
	v_max3_f32 v66, v66, v84, v67
	v_max3_f32 v67, v102, v87, v103
	v_max3_f32 v66, v66, v86, v67
	v_max3_f32 v67, v104, v89, v105
	v_max3_f32 v66, v66, v88, v67
	v_max3_f32 v67, v106, v91, v107
	v_max3_f32 v66, v66, v90, v67
	v_max3_f32 v67, v108, v93, v109
	v_max3_f32 v66, v66, v92, v67
	v_max3_f32 v67, v110, v95, v111
	v_max3_f32 v66, v66, v94, v67
	v_max3_f32 v67, v112, v97, v113
	v_max3_f32 v66, v66, v96, v67
	v_mov_b32_e32 v67, v66
	s_nop 1
	v_permlane32_swap_b32_e32 v66, v67
	v_max_f32_e32 v67, v67, v67
	v_max_f32_e32 v66, v66, v66
	v_max_f32_e32 v66, v66, v67
	v_cmp_lt_f32_e32 vcc, s57, v66
	s_nop 1
	v_cndmask_b32_e32 v68, 0, v66, vcc
	v_sub_f32_e32 v66, v82, v68
	v_exp_f32_e32 v116, v66
	v_sub_f32_e32 v66, v98, v68
	v_exp_f32_e32 v117, v66
	v_sub_f32_e32 v66, v83, v68
	v_exp_f32_e32 v118, v66
	v_sub_f32_e32 v66, v99, v68
	v_exp_f32_e32 v119, v66
	v_sub_f32_e32 v66, v84, v68
	v_exp_f32_e32 v114, v66
	v_sub_f32_e32 v66, v100, v68
	v_exp_f32_e32 v82, v66
	v_add_f32_e32 v66, v116, v117
	v_add_f32_e32 v83, 0, v66
	v_add_f32_e32 v115, v118, v119
	v_pk_add_f32 v[66:67], v[114:115], v[82:83]
	v_cvt_pk_bf16_f32 v162, v116, v118
	v_pk_add_f32 v[98:99], v[66:67], v[66:67] op_sel_hi:[0,1]
	v_sub_f32_e32 v66, v85, v68
	v_exp_f32_e32 v83, v66
	v_sub_f32_e32 v66, v101, v68
	v_exp_f32_e32 v115, v66
	v_sub_f32_e32 v66, v86, v68
	v_exp_f32_e32 v100, v66
	v_sub_f32_e32 v66, v102, v68
	v_exp_f32_e32 v98, v66
	v_add_f32_e32 v101, v83, v115
	v_cvt_pk_bf16_f32 v163, v114, v83
	v_cvt_pk_bf16_f32 v178, v117, v119
	v_pk_add_f32 v[66:67], v[100:101], v[98:99]
	v_cvt_pk_bf16_f32 v179, v82, v115
	v_pk_add_f32 v[84:85], v[66:67], v[66:67] op_sel_hi:[0,1]
	v_sub_f32_e32 v66, v87, v68
	v_exp_f32_e32 v99, v66
	v_sub_f32_e32 v66, v103, v68
	v_exp_f32_e32 v101, v66
	v_sub_f32_e32 v66, v88, v68
	v_exp_f32_e32 v102, v66
	v_sub_f32_e32 v66, v104, v68
	v_exp_f32_e32 v84, v66
	v_add_f32_e32 v103, v99, v101
	v_cvt_pk_bf16_f32 v164, v100, v99
	v_cvt_pk_bf16_f32 v180, v98, v101
	v_pk_add_f32 v[66:67], v[102:103], v[84:85]
	s_nop 0
	v_pk_add_f32 v[86:87], v[66:67], v[66:67] op_sel_hi:[0,1]
	v_sub_f32_e32 v66, v89, v68
	v_exp_f32_e32 v85, v66
	v_sub_f32_e32 v66, v105, v68
	v_exp_f32_e32 v103, v66
	v_sub_f32_e32 v66, v90, v68
	v_exp_f32_e32 v104, v66
	v_sub_f32_e32 v66, v106, v68
	v_exp_f32_e32 v86, v66
	v_add_f32_e32 v105, v85, v103
	v_cvt_pk_bf16_f32 v165, v102, v85
	v_cvt_pk_bf16_f32 v181, v84, v103
	v_pk_add_f32 v[66:67], v[104:105], v[86:87]
	s_nop 0
	v_pk_add_f32 v[88:89], v[66:67], v[66:67] op_sel_hi:[0,1]
	v_sub_f32_e32 v66, v91, v68
	v_exp_f32_e32 v87, v66
	v_sub_f32_e32 v66, v107, v68
	v_exp_f32_e32 v105, v66
	v_sub_f32_e32 v66, v92, v68
	v_exp_f32_e32 v90, v66
	v_sub_f32_e32 v66, v108, v68
	v_exp_f32_e32 v88, v66
	v_sub_f32_e32 v66, v97, v68
	v_add_f32_e32 v91, v87, v105
	v_exp_f32_e32 v97, v66
	v_pk_add_f32 v[66:67], v[90:91], v[88:89]
	v_cvt_pk_bf16_f32 v170, v104, v87
	v_pk_add_f32 v[106:107], v[66:67], v[66:67] op_sel_hi:[0,1]
	v_sub_f32_e32 v66, v93, v68
	v_exp_f32_e32 v89, v66
	v_sub_f32_e32 v66, v109, v68
	v_exp_f32_e32 v91, v66
	v_sub_f32_e32 v66, v94, v68
	v_exp_f32_e32 v92, v66
	v_sub_f32_e32 v66, v110, v68
	v_exp_f32_e32 v106, v66
	v_sub_f32_e32 v66, v113, v68
	v_add_f32_e32 v93, v89, v91
	v_exp_f32_e32 v110, v66
	v_pk_add_f32 v[66:67], v[92:93], v[106:107]
	v_cvt_pk_bf16_f32 v171, v90, v89
	v_pk_add_f32 v[108:109], v[66:67], v[66:67] op_sel_hi:[0,1]
	v_sub_f32_e32 v66, v95, v68
	v_exp_f32_e32 v93, v66
	v_sub_f32_e32 v66, v111, v68
	v_exp_f32_e32 v107, v66
	v_sub_f32_e32 v66, v96, v68
	v_exp_f32_e32 v94, v66
	v_sub_f32_e32 v66, v112, v68
	v_exp_f32_e32 v108, v66
	v_add_f32_e32 v95, v93, v107
	v_exp_f32_e64 v96, -v68
	v_add_f32_e32 v212, v97, v110
	v_pk_add_f32 v[66:67], v[94:95], v[108:109]
	v_cvt_pk_bf16_f32 v172, v92, v93
	v_pk_add_f32 v[66:67], v[66:67], v[66:67] op_sel:[0,1] op_sel_hi:[1,0]
	v_pk_mul_f32 v[48:49], v[48:49], v[96:97] op_sel_hi:[1,0]
	v_mov_b32_e32 v67, v68
	v_pk_add_f32 v[212:213], v[212:213], v[66:67]
	v_pk_mul_f32 v[46:47], v[46:47], v[96:97] op_sel_hi:[1,0]
	v_xor_b32_e32 v66, 0x80000000, v213
	v_mov_b32_e32 v67, v66
	v_mov_b32_e32 v68, v66
	v_mov_b32_e32 v69, v66
	v_mov_b32_e32 v70, v66
	v_mov_b32_e32 v71, v66
	v_mov_b32_e32 v72, v66
	v_mov_b32_e32 v73, v66
	v_mov_b32_e32 v74, v66
	v_mov_b32_e32 v75, v66
	v_mov_b32_e32 v76, v66
	v_mov_b32_e32 v77, v66
	v_mov_b32_e32 v78, v66
	v_mov_b32_e32 v79, v66
	v_mov_b32_e32 v80, v66
	v_mov_b32_e32 v81, v66
	v_pk_mul_f32 v[44:45], v[44:45], v[96:97] op_sel_hi:[1,0]
	v_pk_mul_f32 v[42:43], v[42:43], v[96:97] op_sel_hi:[1,0]
	v_pk_mul_f32 v[40:41], v[40:41], v[96:97] op_sel_hi:[1,0]
	v_pk_mul_f32 v[38:39], v[38:39], v[96:97] op_sel_hi:[1,0]
	v_pk_mul_f32 v[36:37], v[36:37], v[96:97] op_sel_hi:[1,0]
	v_pk_mul_f32 v[34:35], v[34:35], v[96:97] op_sel_hi:[1,0]
	v_pk_mul_f32 v[64:65], v[64:65], v[96:97] op_sel_hi:[1,0]
	v_pk_mul_f32 v[62:63], v[62:63], v[96:97] op_sel_hi:[1,0]
	v_pk_mul_f32 v[60:61], v[60:61], v[96:97] op_sel_hi:[1,0]
	v_pk_mul_f32 v[58:59], v[58:59], v[96:97] op_sel_hi:[1,0]
	v_pk_mul_f32 v[56:57], v[56:57], v[96:97] op_sel_hi:[1,0]
	v_pk_mul_f32 v[54:55], v[54:55], v[96:97] op_sel_hi:[1,0]
	v_pk_mul_f32 v[52:53], v[52:53], v[96:97] op_sel_hi:[1,0]
	v_pk_mul_f32 v[50:51], v[50:51], v[96:97] op_sel_hi:[1,0]
	v_pk_mul_f32 v[32:33], v[32:33], v[96:97] op_sel_hi:[1,0]
	v_pk_mul_f32 v[30:31], v[30:31], v[96:97] op_sel_hi:[1,0]
	v_pk_mul_f32 v[28:29], v[28:29], v[96:97] op_sel_hi:[1,0]
	v_pk_mul_f32 v[26:27], v[26:27], v[96:97] op_sel_hi:[1,0]
	v_pk_mul_f32 v[24:25], v[24:25], v[96:97] op_sel_hi:[1,0]
	v_pk_mul_f32 v[22:23], v[22:23], v[96:97] op_sel_hi:[1,0]
	v_pk_mul_f32 v[20:21], v[20:21], v[96:97] op_sel_hi:[1,0]
	v_pk_mul_f32 v[18:19], v[18:19], v[96:97] op_sel_hi:[1,0]
	v_pk_mul_f32 v[16:17], v[16:17], v[96:97] op_sel_hi:[1,0]
	v_pk_mul_f32 v[14:15], v[14:15], v[96:97] op_sel_hi:[1,0]
	v_pk_mul_f32 v[12:13], v[12:13], v[96:97] op_sel_hi:[1,0]
	v_pk_mul_f32 v[10:11], v[10:11], v[96:97] op_sel_hi:[1,0]
	v_pk_mul_f32 v[8:9], v[8:9], v[96:97] op_sel_hi:[1,0]
	v_pk_mul_f32 v[6:7], v[6:7], v[96:97] op_sel_hi:[1,0]
	v_pk_mul_f32 v[4:5], v[4:5], v[96:97] op_sel_hi:[1,0]
	v_pk_mul_f32 v[2:3], v[2:3], v[96:97] op_sel_hi:[1,0]
	v_mul_f32_e32 v242, v242, v96
	v_cvt_pk_bf16_f32 v173, v94, v97
	v_cvt_pk_bf16_f32 v186, v86, v105
	v_cvt_pk_bf16_f32 v187, v88, v91
	v_cvt_pk_bf16_f32 v188, v106, v107
	v_cvt_pk_bf16_f32 v189, v108, v110

.LBB0_271:
	s_barrier
	s_cmp_lt_u32 s21, s19
	s_mov_b64 s[26:27], -1
	s_cbranch_scc1 .LBB0_277
	s_add_i32 s21, s22, 2
	s_cmp_ge_u32 s21, s18
	s_cbranch_scc1 .LBB0_274
	s_lshl_b32 s26, s28, 14
	s_add_i32 s26, s10, s26
	s_add_i32 s27, s26, 0x2000
	s_mov_b32 m0, s26
	s_add_u32 s100, s8, s80
	s_addc_u32 s101, s9, s81
	global_load_lds_dwordx4 v214, s[100:101]
	s_mov_b32 m0, s27
	s_add_u32 s100, s8, s62
	s_addc_u32 s101, s9, s63
	global_load_lds_dwordx4 v214, s[100:101]
.LBB0_274:
	s_andn2_b64 vcc, exec, s[44:45]
	s_cbranch_vccnz .LBB0_276
	s_lshl_b32 s26, s23, 14
	s_add_i32 s26, s10, s26
	s_add_u32 s100, s8, s96
	s_addc_u32 s101, s9, s97
	s_add_i32 m0, s26, 0xc000
	s_add_i32 s26, s26, 0xe000
	global_load_lds_dwordx4 v216, s[100:101]
	s_mov_b32 m0, s26
	s_add_u32 s100, s8, s58
	s_addc_u32 s101, s9, s59
	global_load_lds_dwordx4 v216, s[100:101]

.LBB0_277:
	s_and_b64 vcc, exec, s[26:27]
	s_cbranch_vccz .LBB0_303
	s_lshl_b32 s21, s33, 14
	s_add_i32 s36, s21, 0
	s_mov_b64 s[26:27], -1
	s_cmp_ge_u32 s22, s19
	v_add_u32_e32 v212, s36, v245
	v_add_u32_e32 v0, s36, v246
	s_cbranch_scc0 .LBB0_288
	ds_read_b128 v[98:101], v212 offset:49152
	ds_read_b128 v[114:117], v212 offset:53248
	ds_read_b128 v[130:133], v212 offset:57344
	ds_read_b128 v[194:197], v212 offset:61440
	s_waitcnt lgkmcnt(0)
	v_mfma_f32_32x32x16_bf16 v[82:97], v[98:101], v[162:165], v[50:65]
	ds_read_b128 v[206:209], v0 offset:49152
	v_mfma_f32_32x32x16_bf16 v[98:113], v[114:117], v[162:165], v[34:49]
	ds_read_b128 v[198:201], v0 offset:53248
	s_add_i32 s21, s22, 2
	s_cmp_lt_u32 s21, s18
	s_cselect_b64 s[26:27], -1, 0
	s_cmp_ge_u32 s21, s18
	s_cbranch_scc1 .LBB0_281
	s_lshl_b32 s37, s28, 14
	s_add_i32 m0, s10, s37
	s_add_u32 s100, s8, s80
	s_addc_u32 s101, s9, s81
	global_load_lds_dwordx4 v214, s[100:101]
.LBB0_281:
	v_mfma_f32_32x32x16_bf16 v[114:129], v[130:133], v[162:165], v[18:33]
	ds_read_b128 v[202:205], v0 offset:57344
	v_mfma_f32_32x32x16_bf16 v[130:145], v[194:197], v[162:165], v[2:17]
	ds_read_b128 v[194:197], v0 offset:61440
	s_waitcnt lgkmcnt(0)
	v_mfma_f32_32x32x16_bf16 v[82:97], v[206:209], v[170:173], v[82:97]
	v_add_u32_e32 v250, s36, v247
	ds_read_b128 v[206:209], v250 offset:49152
	v_mfma_f32_32x32x16_bf16 v[98:113], v[198:201], v[170:173], v[98:113]
	ds_read_b128 v[198:201], v250 offset:53248
	s_andn2_b64 vcc, exec, s[26:27]
	s_cbranch_vccnz .LBB0_283
	s_lshl_b32 s26, s28, 14
	s_add_i32 s26, s10, s26
	s_add_i32 m0, s26, 0x2000
	s_add_u32 s100, s8, s62
	s_addc_u32 s101, s9, s63
	global_load_lds_dwordx4 v214, s[100:101]
.LBB0_283:
	v_mfma_f32_32x32x16_bf16 v[114:129], v[202:205], v[170:173], v[114:129]
	ds_read_b128 v[202:205], v250 offset:57344
	v_mfma_f32_32x32x16_bf16 v[130:145], v[194:197], v[170:173], v[130:145]
	ds_read_b128 v[194:197], v250 offset:61440
	s_waitcnt lgkmcnt(0)
	v_mfma_f32_32x32x16_bf16 v[82:97], v[206:209], v[178:181], v[82:97]
	v_add_u32_e32 v250, s36, v248
	ds_read_b128 v[206:209], v250 offset:49152
	v_mfma_f32_32x32x16_bf16 v[98:113], v[198:201], v[178:181], v[98:113]
	ds_read_b128 v[198:201], v250 offset:53248
	v_cndmask_b32_e64 v224, 0, 1, s[44:45]
	v_cmp_ne_u32_e64 s[40:41], 1, v224
	s_andn2_b64 vcc, exec, s[44:45]
	s_cbranch_vccnz .LBB0_285
	s_lshl_b32 s26, s23, 14
	s_add_i32 s26, s10, s26
	s_add_i32 m0, s26, 0xc000
	s_add_u32 s100, s8, s96
	s_addc_u32 s101, s9, s97
	global_load_lds_dwordx4 v216, s[100:101]
.LBB0_285:
	v_mfma_f32_32x32x16_bf16 v[114:129], v[202:205], v[178:181], v[114:129]
	ds_read_b128 v[202:205], v250 offset:57344
	v_mfma_f32_32x32x16_bf16 v[130:145], v[194:197], v[178:181], v[130:145]
	ds_read_b128 v[194:197], v250 offset:61440
	s_waitcnt lgkmcnt(0)
	v_mfma_f32_32x32x16_bf16 v[82:97], v[206:209], v[186:189], v[82:97]
	v_mfma_f32_32x32x16_bf16 v[98:113], v[198:201], v[186:189], v[98:113]
	s_and_b64 vcc, exec, s[40:41]
	s_cbranch_vccnz .LBB0_287
	s_lshl_b32 s26, s23, 14
	s_add_i32 s26, s10, s26
	s_add_i32 m0, s26, 0xe000
	s_add_u32 s100, s8, s58
	s_addc_u32 s101, s9, s59
	global_load_lds_dwordx4 v216, s[100:101]

.LBB0_291:
	s_waitcnt lgkmcnt(0)
	v_mfma_f32_32x32x16_bf16 v[50:65], v[126:129], v[162:165], v[50:65]
	ds_read_b128 v[126:129], v0 offset:49152
	s_nop 1
	v_exp_f32_e32 v130, v82
	v_exp_f32_e32 v131, v83
	v_add_f32_e32 v132, v1, v130
	v_add_f32_e32 v133, v1, v131
	v_cvt_pk_bf16_f32 v166, v130, v131
	v_mfma_f32_32x32x16_bf16 v[34:49], v[122:125], v[162:165], v[34:49]
	ds_read_b128 v[122:125], v0 offset:53248
	v_exp_f32_e32 v134, v84
	v_exp_f32_e32 v135, v85
	s_add_i32 s21, s22, 2
	s_cmp_lt_u32 s21, s18
	v_add_f32_e32 v130, v132, v134
	v_add_f32_e32 v131, v133, v135
	v_cvt_pk_bf16_f32 v167, v134, v135
	s_cselect_b64 s[26:27], -1, 0
	s_cmp_ge_u32 s21, s18
	s_cbranch_scc1 .LBB0_293
	s_lshl_b32 s37, s28, 14
	s_add_i32 m0, s10, s37
	s_add_u32 s100, s8, s80
	s_addc_u32 s101, s9, s81
	global_load_lds_dwordx4 v214, s[100:101]
.LBB0_293:
	v_mfma_f32_32x32x16_bf16 v[18:33], v[118:121], v[162:165], v[18:33]
	ds_read_b128 v[118:121], v0 offset:57344
	v_exp_f32_e32 v132, v86
	v_exp_f32_e32 v133, v87
	v_add_f32_e32 v130, v130, v132
	v_add_f32_e32 v131, v131, v133
	v_cvt_pk_bf16_f32 v168, v132, v133
	v_mfma_f32_32x32x16_bf16 v[2:17], v[114:117], v[162:165], v[2:17]
	ds_read_b128 v[114:117], v0 offset:61440
	v_exp_f32_e32 v0, v88
	v_exp_f32_e32 v132, v89
	v_add_f32_e32 v130, v130, v0
	v_add_f32_e32 v131, v131, v132
	v_cvt_pk_bf16_f32 v169, v0, v132
	s_waitcnt lgkmcnt(0)
	v_mfma_f32_32x32x16_bf16 v[50:65], v[126:129], v[170:173], v[50:65]
	v_add_u32_e32 v0, s36, v247
	ds_read_b128 v[126:129], v0 offset:49152
	v_exp_f32_e32 v132, v90
	v_exp_f32_e32 v133, v91
	v_add_f32_e32 v130, v130, v132
	v_add_f32_e32 v131, v131, v133
	v_cvt_pk_bf16_f32 v174, v132, v133
	v_mfma_f32_32x32x16_bf16 v[34:49], v[122:125], v[170:173], v[34:49]
	ds_read_b128 v[122:125], v0 offset:53248
	v_exp_f32_e32 v132, v92
	v_exp_f32_e32 v133, v93
	v_add_f32_e32 v130, v130, v132
	v_add_f32_e32 v131, v131, v133
	s_andn2_b64 vcc, exec, s[26:27]
	v_cvt_pk_bf16_f32 v175, v132, v133
	s_cbranch_vccnz .LBB0_295
	s_lshl_b32 s26, s28, 14
	s_add_i32 s26, s10, s26
	s_add_i32 m0, s26, 0x2000
	s_add_u32 s100, s8, s62
	s_addc_u32 s101, s9, s63
	global_load_lds_dwordx4 v214, s[100:101]
.LBB0_295:
	v_mfma_f32_32x32x16_bf16 v[18:33], v[118:121], v[170:173], v[18:33]
	ds_read_b128 v[118:121], v0 offset:57344
	v_exp_f32_e32 v132, v94
	v_exp_f32_e32 v133, v95
	v_add_f32_e32 v130, v130, v132
	v_add_f32_e32 v131, v131, v133
	v_cvt_pk_bf16_f32 v176, v132, v133
	v_mfma_f32_32x32x16_bf16 v[2:17], v[114:117], v[170:173], v[2:17]
	ds_read_b128 v[114:117], v0 offset:61440
	v_exp_f32_e32 v0, v96
	v_exp_f32_e32 v132, v97
	v_add_f32_e32 v130, v130, v0
	v_add_f32_e32 v131, v131, v132
	v_cvt_pk_bf16_f32 v177, v0, v132
	s_waitcnt lgkmcnt(0)
	v_mfma_f32_32x32x16_bf16 v[50:65], v[126:129], v[178:181], v[50:65]
	v_add_u32_e32 v0, s36, v248
	ds_read_b128 v[126:129], v0 offset:49152
	v_exp_f32_e32 v132, v98
	v_exp_f32_e32 v133, v99
	v_add_f32_e32 v130, v130, v132
	v_add_f32_e32 v131, v131, v133
	v_cvt_pk_bf16_f32 v182, v132, v133
	v_mfma_f32_32x32x16_bf16 v[34:49], v[122:125], v[178:181], v[34:49]
	v_exp_f32_e32 v132, v100
	v_exp_f32_e32 v133, v101
	ds_read_b128 v[122:125], v0 offset:53248
	v_add_f32_e32 v130, v130, v132
	v_add_f32_e32 v131, v131, v133
	v_cvt_pk_bf16_f32 v183, v132, v133
	v_cndmask_b32_e64 v132, 0, 1, s[44:45]
	v_cmp_ne_u32_e64 s[40:41], 1, v132
	s_andn2_b64 vcc, exec, s[44:45]
	s_cbranch_vccnz .LBB0_297
	s_lshl_b32 s26, s23, 14
	s_add_i32 s26, s10, s26
	s_add_i32 m0, s26, 0xc000
	s_add_u32 s100, s8, s96
	s_addc_u32 s101, s9, s97
	global_load_lds_dwordx4 v216, s[100:101]
.LBB0_297:
	v_mfma_f32_32x32x16_bf16 v[18:33], v[118:121], v[178:181], v[18:33]
	ds_read_b128 v[118:121], v0 offset:57344
	v_exp_f32_e32 v132, v102
	v_exp_f32_e32 v133, v103
	v_add_f32_e32 v130, v130, v132
	v_add_f32_e32 v131, v131, v133
	v_cvt_pk_bf16_f32 v184, v132, v133
	v_mfma_f32_32x32x16_bf16 v[2:17], v[114:117], v[178:181], v[2:17]
	ds_read_b128 v[114:117], v0 offset:61440
	v_exp_f32_e32 v0, v104
	v_exp_f32_e32 v132, v105
	v_add_f32_e32 v130, v130, v0
	v_add_f32_e32 v131, v131, v132
	v_cvt_pk_bf16_f32 v185, v0, v132
	s_waitcnt lgkmcnt(0)
	v_mfma_f32_32x32x16_bf16 v[50:65], v[126:129], v[186:189], v[50:65]
	v_exp_f32_e32 v0, v106
	v_exp_f32_e32 v126, v107
	v_add_f32_e32 v127, v130, v0
	v_add_f32_e32 v128, v131, v126
	v_cvt_pk_bf16_f32 v190, v0, v126
	v_mfma_f32_32x32x16_bf16 v[34:49], v[122:125], v[186:189], v[34:49]
	v_exp_f32_e32 v123, v108
	v_exp_f32_e32 v124, v109
	v_add_f32_e32 v0, v127, v123
	v_add_f32_e32 v122, v128, v124
	s_and_b64 vcc, exec, s[40:41]
	v_cvt_pk_bf16_f32 v191, v123, v124
	s_cbranch_vccnz .LBB0_299
	s_lshl_b32 s26, s23, 14
	s_add_i32 s26, s10, s26
	s_add_i32 m0, s26, 0xe000
	s_add_u32 s100, s8, s58
	s_addc_u32 s101, s9, s59
	global_load_lds_dwordx4 v216, s[100:101]
.LBB0_299:
	v_mfma_f32_32x32x16_bf16 v[18:33], v[118:121], v[186:189], v[18:33]
	v_exp_f32_e32 v118, v110
	v_exp_f32_e32 v119, v111
	v_add_f32_e32 v0, v0, v118
	v_add_f32_e32 v120, v122, v119
	v_cvt_pk_bf16_f32 v192, v118, v119
	v_mfma_f32_32x32x16_bf16 v[2:17], v[114:117], v[186:189], v[2:17]
	v_exp_f32_e32 v114, v112
	v_exp_f32_e32 v115, v113
	v_add_f32_e32 v0, v0, v114
	v_add_f32_e32 v116, v120, v115
	v_cvt_pk_bf16_f32 v193, v114, v115
	v_add_f32_e32 v212, v0, v116
	v_cmp_nge_f32_e32 vcc, s7, v212
	s_cbranch_vccz .LBB0_301
	v_max_f32_e32 v0, v99, v99
	v_max_f32_e32 v66, v83, v83
	v_max_f32_e32 v0, v66, v0
	v_max3_f32 v0, v82, v98, v0
	v_max3_f32 v66, v100, v85, v101
	v_max3_f32 v0, v0, v84, v66
	v_max3_f32 v66, v102, v87, v103
	v_max3_f32 v0, v0, v86, v66
	v_max3_f32 v66, v104, v89, v105
	v_max3_f32 v0, v0, v88, v66
	v_max3_f32 v66, v106, v91, v107
	v_max3_f32 v0, v0, v90, v66
	v_max3_f32 v66, v108, v93, v109
	v_max3_f32 v0, v0, v92, v66
	v_max3_f32 v66, v110, v95, v111
	v_max3_f32 v0, v0, v94, v66
	v_max3_f32 v66, v112, v97, v113
	v_max3_f32 v0, v0, v96, v66
	v_mov_b32_e32 v66, v0
	s_nop 1
	v_permlane32_swap_b32_e32 v0, v66
	v_max_f32_e32 v66, v66, v66
	v_max_f32_e32 v0, v0, v0
	v_max_f32_e32 v0, v0, v66
	v_cmp_lt_f32_e32 vcc, s57, v0
	s_nop 1
	v_cndmask_b32_e32 v68, 0, v0, vcc
	v_sub_f32_e32 v0, v82, v68
	v_exp_f32_e32 v116, v0
	v_sub_f32_e32 v0, v98, v68
	v_exp_f32_e32 v117, v0
	v_sub_f32_e32 v0, v83, v68
	v_exp_f32_e32 v118, v0
	v_sub_f32_e32 v0, v99, v68
	v_exp_f32_e32 v119, v0
	v_sub_f32_e32 v0, v84, v68
	v_exp_f32_e32 v98, v0
	v_sub_f32_e32 v0, v100, v68
	v_exp_f32_e32 v82, v0
	v_add_f32_e32 v0, v117, v116
	v_add_f32_e32 v99, 0, v0
	v_add_f32_e32 v83, v119, v118
	v_sub_f32_e32 v0, v85, v68
	v_pk_add_f32 v[66:67], v[82:83], v[98:99]
	v_exp_f32_e32 v83, v0
	v_sub_f32_e32 v0, v101, v68
	v_pk_add_f32 v[114:115], v[66:67], v[66:67] op_sel_hi:[0,1]
	v_exp_f32_e32 v99, v0
	v_sub_f32_e32 v0, v86, v68
	v_exp_f32_e32 v114, v0
	v_sub_f32_e32 v0, v102, v68
	v_exp_f32_e32 v84, v0
	v_add_f32_e32 v85, v99, v83
	v_sub_f32_e32 v0, v87, v68
	v_cvt_pk_bf16_f32 v166, v116, v118
	v_pk_add_f32 v[66:67], v[84:85], v[114:115]
	v_exp_f32_e32 v85, v0
	v_sub_f32_e32 v0, v103, v68
	v_pk_add_f32 v[100:101], v[66:67], v[66:67] op_sel_hi:[0,1]
	v_exp_f32_e32 v115, v0
	v_sub_f32_e32 v0, v88, v68
	v_exp_f32_e32 v100, v0
	v_sub_f32_e32 v0, v104, v68
	v_exp_f32_e32 v86, v0
	v_add_f32_e32 v87, v115, v85
	v_sub_f32_e32 v0, v89, v68
	v_cvt_pk_bf16_f32 v167, v98, v83
	v_pk_add_f32 v[66:67], v[86:87], v[100:101]
	v_exp_f32_e32 v87, v0
	v_sub_f32_e32 v0, v105, v68
	v_pk_add_f32 v[102:103], v[66:67], v[66:67] op_sel_hi:[0,1]
	v_exp_f32_e32 v101, v0
	v_sub_f32_e32 v0, v90, v68
	v_exp_f32_e32 v102, v0
	v_sub_f32_e32 v0, v106, v68
	v_exp_f32_e32 v88, v0
	v_add_f32_e32 v89, v101, v87
	v_sub_f32_e32 v0, v91, v68
	v_cvt_pk_bf16_f32 v168, v114, v85
	v_pk_add_f32 v[66:67], v[88:89], v[102:103]
	v_exp_f32_e32 v89, v0
	v_sub_f32_e32 v0, v107, v68
	v_pk_add_f32 v[104:105], v[66:67], v[66:67] op_sel_hi:[0,1]
	v_exp_f32_e32 v103, v0
	v_sub_f32_e32 v0, v92, v68
	v_exp_f32_e32 v104, v0
	v_sub_f32_e32 v0, v108, v68
	v_exp_f32_e32 v90, v0
	v_sub_f32_e32 v0, v97, v68
	v_exp_f32_e32 v97, v0
	v_add_f32_e32 v91, v103, v89
	v_sub_f32_e32 v0, v93, v68
	v_pk_add_f32 v[66:67], v[90:91], v[104:105]
	v_exp_f32_e32 v91, v0
	v_sub_f32_e32 v0, v109, v68
	v_pk_add_f32 v[106:107], v[66:67], v[66:67] op_sel_hi:[0,1]
	v_exp_f32_e32 v105, v0
	v_sub_f32_e32 v0, v94, v68
	v_exp_f32_e32 v106, v0
	v_sub_f32_e32 v0, v110, v68
	v_exp_f32_e32 v92, v0
	v_sub_f32_e32 v0, v113, v68
	v_exp_f32_e32 v110, v0
	v_add_f32_e32 v93, v105, v91
	v_sub_f32_e32 v0, v95, v68
	v_pk_add_f32 v[66:67], v[92:93], v[106:107]
	v_exp_f32_e32 v93, v0
	v_sub_f32_e32 v0, v111, v68
	v_pk_add_f32 v[108:109], v[66:67], v[66:67] op_sel_hi:[0,1]
	v_exp_f32_e32 v107, v0
	v_sub_f32_e32 v0, v96, v68
	v_exp_f32_e32 v108, v0
	v_sub_f32_e32 v0, v112, v68
	v_exp_f32_e32 v94, v0
	v_add_f32_e32 v95, v107, v93
	v_exp_f32_e64 v0, -v68
	v_add_f32_e32 v212, v110, v97
	v_pk_add_f32 v[66:67], v[94:95], v[108:109]
	v_cvt_pk_bf16_f32 v169, v100, v87
	v_pk_add_f32 v[66:67], v[66:67], v[66:67] op_sel:[0,1] op_sel_hi:[1,0]
	v_pk_mul_f32 v[64:65], v[64:65], v[0:1] op_sel_hi:[1,0]
	v_mov_b32_e32 v67, v68
	v_pk_add_f32 v[212:213], v[212:213], v[66:67]
	v_pk_mul_f32 v[62:63], v[62:63], v[0:1] op_sel_hi:[1,0]
	v_xor_b32_e32 v66, 0x80000000, v213
	v_mov_b32_e32 v67, v66
	v_mov_b32_e32 v68, v66
	v_mov_b32_e32 v69, v66
	v_mov_b32_e32 v70, v66
	v_mov_b32_e32 v71, v66
	v_mov_b32_e32 v72, v66
	v_mov_b32_e32 v73, v66
	v_mov_b32_e32 v74, v66
	v_mov_b32_e32 v75, v66
	v_mov_b32_e32 v76, v66
	v_mov_b32_e32 v77, v66
	v_mov_b32_e32 v78, v66
	v_mov_b32_e32 v79, v66
	v_mov_b32_e32 v80, v66
	v_mov_b32_e32 v81, v66
	v_pk_mul_f32 v[60:61], v[60:61], v[0:1] op_sel_hi:[1,0]
	v_pk_mul_f32 v[58:59], v[58:59], v[0:1] op_sel_hi:[1,0]
	v_pk_mul_f32 v[56:57], v[56:57], v[0:1] op_sel_hi:[1,0]
	v_pk_mul_f32 v[54:55], v[54:55], v[0:1] op_sel_hi:[1,0]
	v_pk_mul_f32 v[52:53], v[52:53], v[0:1] op_sel_hi:[1,0]
	v_pk_mul_f32 v[50:51], v[50:51], v[0:1] op_sel_hi:[1,0]
	v_pk_mul_f32 v[48:49], v[48:49], v[0:1] op_sel_hi:[1,0]
	v_pk_mul_f32 v[46:47], v[46:47], v[0:1] op_sel_hi:[1,0]
	v_pk_mul_f32 v[44:45], v[44:45], v[0:1] op_sel_hi:[1,0]
	v_pk_mul_f32 v[42:43], v[42:43], v[0:1] op_sel_hi:[1,0]
	v_pk_mul_f32 v[40:41], v[40:41], v[0:1] op_sel_hi:[1,0]
	v_pk_mul_f32 v[38:39], v[38:39], v[0:1] op_sel_hi:[1,0]
	v_pk_mul_f32 v[36:37], v[36:37], v[0:1] op_sel_hi:[1,0]
	v_pk_mul_f32 v[34:35], v[34:35], v[0:1] op_sel_hi:[1,0]
	v_pk_mul_f32 v[32:33], v[32:33], v[0:1] op_sel_hi:[1,0]
	v_pk_mul_f32 v[30:31], v[30:31], v[0:1] op_sel_hi:[1,0]
	v_pk_mul_f32 v[28:29], v[28:29], v[0:1] op_sel_hi:[1,0]
	v_pk_mul_f32 v[26:27], v[26:27], v[0:1] op_sel_hi:[1,0]
	v_pk_mul_f32 v[24:25], v[24:25], v[0:1] op_sel_hi:[1,0]
	v_pk_mul_f32 v[22:23], v[22:23], v[0:1] op_sel_hi:[1,0]
	v_pk_mul_f32 v[20:21], v[20:21], v[0:1] op_sel_hi:[1,0]
	v_pk_mul_f32 v[18:19], v[18:19], v[0:1] op_sel_hi:[1,0]
	v_pk_mul_f32 v[16:17], v[16:17], v[0:1] op_sel_hi:[1,0]
	v_pk_mul_f32 v[14:15], v[14:15], v[0:1] op_sel_hi:[1,0]
	v_pk_mul_f32 v[12:13], v[12:13], v[0:1] op_sel_hi:[1,0]
	v_pk_mul_f32 v[10:11], v[10:11], v[0:1] op_sel_hi:[1,0]
	v_pk_mul_f32 v[8:9], v[8:9], v[0:1] op_sel_hi:[1,0]
	v_pk_mul_f32 v[6:7], v[6:7], v[0:1] op_sel_hi:[1,0]
	v_pk_mul_f32 v[4:5], v[4:5], v[0:1] op_sel_hi:[1,0]
	v_pk_mul_f32 v[2:3], v[2:3], v[0:1] op_sel_hi:[1,0]
	v_mul_f32_e32 v243, v243, v0
	v_cvt_pk_bf16_f32 v174, v102, v89
	v_cvt_pk_bf16_f32 v175, v104, v91
	v_cvt_pk_bf16_f32 v176, v106, v93
	v_cvt_pk_bf16_f32 v177, v108, v97
	v_cvt_pk_bf16_f32 v182, v117, v119
	v_cvt_pk_bf16_f32 v183, v82, v99
	v_cvt_pk_bf16_f32 v184, v84, v115
	v_cvt_pk_bf16_f32 v185, v86, v101
	v_cvt_pk_bf16_f32 v190, v88, v103
	v_cvt_pk_bf16_f32 v191, v90, v105
	v_cvt_pk_bf16_f32 v192, v92, v107
	v_cvt_pk_bf16_f32 v193, v94, v110

.LBB0_311:
	s_add_i32 s26, s31, 1
	s_cmp_lg_u32 s31, 2
	s_cselect_b32 s31, s26, 0
	s_add_i32 s26, s28, 1
	s_cmp_lg_u32 s28, 2
	s_cselect_b32 s28, s26, 0
	s_add_i32 s26, s33, 1
	s_cmp_lg_u32 s33, 2
	s_cselect_b32 s33, s26, 0
	s_add_i32 s26, s23, 1
	s_barrier
	s_cmp_lg_u32 s23, 2
	s_cselect_b32 s23, s26, 0
	s_cmp_lt_u32 s22, s19
	s_mov_b64 s[26:27], -1
	s_cbranch_scc1 .LBB0_317
	s_add_i32 s26, s22, 3
	s_cmp_gt_u32 s26, s17
	s_cbranch_scc1 .LBB0_314
	s_lshl_b32 s26, s28, 14
	s_add_i32 s26, s10, s26
	s_add_i32 s27, s26, 0x2000
	s_mov_b32 m0, s26
	s_add_u32 s100, s8, s50
	s_addc_u32 s101, s9, s51
	global_load_lds_dwordx4 v214, s[100:101]
	s_mov_b32 m0, s27
	s_add_u32 s100, s8, s4
	s_addc_u32 s101, s9, s5
	global_load_lds_dwordx4 v214, s[100:101]
.LBB0_314:
	s_andn2_b64 vcc, exec, s[44:45]
	s_cbranch_vccnz .LBB0_316
	s_lshl_b32 s26, s23, 14
	s_add_i32 s26, s10, s26
	s_add_u32 s100, s8, s0
	s_addc_u32 s101, s9, s1
	s_add_i32 m0, s26, 0xc000
	s_add_i32 s26, s26, 0xe000
	global_load_lds_dwordx4 v216, s[100:101]
	s_mov_b32 m0, s26
	s_add_u32 s100, s8, s52
	s_addc_u32 s101, s9, s53
	global_load_lds_dwordx4 v216, s[100:101]

.LBB0_317:
	s_and_b64 vcc, exec, s[26:27]
	s_cbranch_vccz .LBB0_343
	s_lshl_b32 s26, s33, 14
	s_add_i32 s37, s22, 1
	s_add_i32 s36, s26, 0
	s_mov_b64 s[26:27], -1
	s_cmp_ge_u32 s37, s19
	v_add_u32_e32 v212, s36, v245
	v_add_u32_e32 v0, s36, v246
	s_cbranch_scc0 .LBB0_328
	ds_read_b128 v[98:101], v212 offset:49152
	ds_read_b128 v[114:117], v212 offset:53248
	ds_read_b128 v[130:133], v212 offset:57344
	ds_read_b128 v[194:197], v212 offset:61440
	s_waitcnt lgkmcnt(0)
	v_mfma_f32_32x32x16_bf16 v[82:97], v[98:101], v[166:169], v[50:65]
	ds_read_b128 v[206:209], v0 offset:49152
	v_mfma_f32_32x32x16_bf16 v[98:113], v[114:117], v[166:169], v[34:49]
	ds_read_b128 v[198:201], v0 offset:53248
	s_add_i32 s37, s22, 3
	s_cmp_le_u32 s37, s17
	s_cselect_b64 s[26:27], -1, 0
	s_cmp_gt_u32 s37, s17
	s_cbranch_scc1 .LBB0_321
	s_lshl_b32 s37, s28, 14
	s_add_i32 m0, s10, s37
	s_add_u32 s100, s8, s50
	s_addc_u32 s101, s9, s51
	global_load_lds_dwordx4 v214, s[100:101]
.LBB0_321:
	v_mfma_f32_32x32x16_bf16 v[114:129], v[130:133], v[166:169], v[18:33]
	ds_read_b128 v[202:205], v0 offset:57344
	v_mfma_f32_32x32x16_bf16 v[130:145], v[194:197], v[166:169], v[2:17]
	ds_read_b128 v[194:197], v0 offset:61440
	s_waitcnt lgkmcnt(0)
	v_mfma_f32_32x32x16_bf16 v[82:97], v[206:209], v[174:177], v[82:97]
	v_add_u32_e32 v250, s36, v247
	ds_read_b128 v[206:209], v250 offset:49152
	v_mfma_f32_32x32x16_bf16 v[98:113], v[198:201], v[174:177], v[98:113]
	ds_read_b128 v[198:201], v250 offset:53248
	s_andn2_b64 vcc, exec, s[26:27]
	s_cbranch_vccnz .LBB0_323
	s_lshl_b32 s26, s28, 14
	s_add_i32 s26, s10, s26
	s_add_i32 m0, s26, 0x2000
	s_add_u32 s100, s8, s4
	s_addc_u32 s101, s9, s5
	global_load_lds_dwordx4 v214, s[100:101]
.LBB0_323:
	v_mfma_f32_32x32x16_bf16 v[114:129], v[202:205], v[174:177], v[114:129]
	ds_read_b128 v[202:205], v250 offset:57344
	v_mfma_f32_32x32x16_bf16 v[130:145], v[194:197], v[174:177], v[130:145]
	ds_read_b128 v[194:197], v250 offset:61440
	s_waitcnt lgkmcnt(0)
	v_mfma_f32_32x32x16_bf16 v[82:97], v[206:209], v[182:185], v[82:97]
	v_add_u32_e32 v250, s36, v248
	ds_read_b128 v[206:209], v250 offset:49152
	v_mfma_f32_32x32x16_bf16 v[98:113], v[198:201], v[182:185], v[98:113]
	ds_read_b128 v[198:201], v250 offset:53248
	v_cndmask_b32_e64 v224, 0, 1, s[44:45]
	v_cmp_ne_u32_e64 s[40:41], 1, v224
	s_andn2_b64 vcc, exec, s[44:45]
	s_cbranch_vccnz .LBB0_325
	s_lshl_b32 s26, s23, 14
	s_add_i32 s26, s10, s26
	s_add_i32 m0, s26, 0xc000
	s_add_u32 s100, s8, s0
	s_addc_u32 s101, s9, s1
	global_load_lds_dwordx4 v216, s[100:101]
.LBB0_325:
	v_mfma_f32_32x32x16_bf16 v[114:129], v[202:205], v[182:185], v[114:129]
	ds_read_b128 v[202:205], v250 offset:57344
	v_mfma_f32_32x32x16_bf16 v[130:145], v[194:197], v[182:185], v[130:145]
	ds_read_b128 v[194:197], v250 offset:61440
	s_waitcnt lgkmcnt(0)
	v_mfma_f32_32x32x16_bf16 v[82:97], v[206:209], v[190:193], v[82:97]
	v_mfma_f32_32x32x16_bf16 v[98:113], v[198:201], v[190:193], v[98:113]
	s_and_b64 vcc, exec, s[40:41]
	s_cbranch_vccnz .LBB0_327
	s_lshl_b32 s26, s23, 14
	s_add_i32 s26, s10, s26
	s_add_i32 m0, s26, 0xe000
	s_add_u32 s100, s8, s52
	s_addc_u32 s101, s9, s53
	global_load_lds_dwordx4 v216, s[100:101]

.LBB0_335:
	v_mfma_f32_32x32x16_bf16 v[18:33], v[118:121], v[174:177], v[18:33]
	ds_read_b128 v[118:121], v0 offset:57344
	v_exp_f32_e32 v130, v94
	v_exp_f32_e32 v131, v95
	v_add_f32_e32 v132, v132, v130
	v_add_f32_e32 v133, v133, v131
	v_cvt_pk_bf16_f32 v172, v130, v131
	v_mfma_f32_32x32x16_bf16 v[2:17], v[114:117], v[174:177], v[2:17]
	ds_read_b128 v[114:117], v0 offset:61440
	v_exp_f32_e32 v0, v96
	v_exp_f32_e32 v130, v97
	v_add_f32_e32 v131, v132, v0
	v_add_f32_e32 v132, v133, v130
	v_cvt_pk_bf16_f32 v173, v0, v130
	s_waitcnt lgkmcnt(0)
	v_mfma_f32_32x32x16_bf16 v[50:65], v[126:129], v[182:185], v[50:65]
	v_add_u32_e32 v0, s36, v248
	ds_read_b128 v[126:129], v0 offset:49152
	v_exp_f32_e32 v130, v98
	v_exp_f32_e32 v133, v99
	v_add_f32_e32 v131, v131, v130
	v_add_f32_e32 v134, v132, v133
	v_cvt_pk_bf16_f32 v178, v130, v133
	v_mfma_f32_32x32x16_bf16 v[34:49], v[122:125], v[182:185], v[34:49]
	v_exp_f32_e32 v130, v100
	v_exp_f32_e32 v135, v101
	ds_read_b128 v[122:125], v0 offset:53248
	v_add_f32_e32 v132, v131, v130
	v_add_f32_e32 v133, v134, v135
	v_cvt_pk_bf16_f32 v179, v130, v135
	v_cndmask_b32_e64 v130, 0, 1, s[44:45]
	v_cmp_ne_u32_e64 s[40:41], 1, v130
	s_andn2_b64 vcc, exec, s[44:45]
	v_lshl_add_u64 v[130:131], s[8:9], 0, v[216:217]
	s_cbranch_vccnz .LBB0_337
	s_lshl_b32 s22, s23, 14
	s_add_i32 s22, s10, s22
	s_add_i32 m0, s22, 0xc000
	s_add_u32 s100, s8, s0
	s_addc_u32 s101, s9, s1
	global_load_lds_dwordx4 v216, s[100:101]

.LBB0_339:
	v_mfma_f32_32x32x16_bf16 v[18:33], v[118:121], v[190:193], v[18:33]
	v_exp_f32_e32 v118, v110
	v_exp_f32_e32 v119, v111
	v_add_f32_e32 v0, v0, v118
	v_add_f32_e32 v120, v122, v119
	v_cvt_pk_bf16_f32 v188, v118, v119
	v_mfma_f32_32x32x16_bf16 v[2:17], v[114:117], v[190:193], v[2:17]
	v_exp_f32_e32 v114, v112
	v_exp_f32_e32 v115, v113
	v_add_f32_e32 v0, v0, v114
	v_add_f32_e32 v116, v120, v115
	v_cvt_pk_bf16_f32 v189, v114, v115
	v_add_f32_e32 v212, v0, v116
	v_cmp_nge_f32_e32 vcc, s7, v212
	s_cbranch_vccz .LBB0_341
	v_max_f32_e32 v0, v99, v99
	v_max_f32_e32 v66, v83, v83
	v_max_f32_e32 v0, v66, v0
	v_max3_f32 v0, v82, v98, v0
	v_max3_f32 v66, v100, v85, v101
	v_max3_f32 v0, v0, v84, v66
	v_max3_f32 v66, v102, v87, v103
	v_max3_f32 v0, v0, v86, v66
	v_max3_f32 v66, v104, v89, v105
	v_max3_f32 v0, v0, v88, v66
	v_max3_f32 v66, v106, v91, v107
	v_max3_f32 v0, v0, v90, v66
	v_max3_f32 v66, v108, v93, v109
	v_max3_f32 v0, v0, v92, v66
	v_max3_f32 v66, v110, v95, v111
	v_max3_f32 v0, v0, v94, v66
	v_max3_f32 v66, v112, v97, v113
	v_max3_f32 v0, v0, v96, v66
	v_mov_b32_e32 v66, v0
	s_nop 1
	v_permlane32_swap_b32_e32 v0, v66
	v_max_f32_e32 v66, v66, v66
	v_max_f32_e32 v0, v0, v0
	v_max_f32_e32 v0, v0, v66
	v_cmp_lt_f32_e32 vcc, s57, v0
	s_nop 1
	v_cndmask_b32_e32 v68, 0, v0, vcc
	v_sub_f32_e32 v0, v82, v68
	v_exp_f32_e32 v116, v0
	v_sub_f32_e32 v0, v98, v68
	v_exp_f32_e32 v117, v0
	v_sub_f32_e32 v0, v83, v68
	v_exp_f32_e32 v118, v0
	v_sub_f32_e32 v0, v99, v68
	v_exp_f32_e32 v119, v0
	v_sub_f32_e32 v0, v84, v68
	v_exp_f32_e32 v114, v0
	v_sub_f32_e32 v0, v100, v68
	v_exp_f32_e32 v82, v0
	v_add_f32_e32 v0, v116, v117
	v_add_f32_e32 v83, 0, v0
	v_add_f32_e32 v115, v118, v119
	v_sub_f32_e32 v0, v85, v68
	v_pk_add_f32 v[66:67], v[114:115], v[82:83]
	v_exp_f32_e32 v83, v0
	v_sub_f32_e32 v0, v101, v68
	v_exp_f32_e32 v115, v0
	v_sub_f32_e32 v0, v86, v68
	v_pk_add_f32 v[98:99], v[66:67], v[66:67] op_sel_hi:[0,1]
	v_exp_f32_e32 v100, v0
	v_sub_f32_e32 v0, v102, v68
	v_exp_f32_e32 v98, v0
	v_add_f32_e32 v101, v83, v115
	v_sub_f32_e32 v0, v87, v68
	v_cvt_pk_bf16_f32 v162, v116, v118
	v_pk_add_f32 v[66:67], v[100:101], v[98:99]
	v_exp_f32_e32 v99, v0
	v_sub_f32_e32 v0, v103, v68
	v_exp_f32_e32 v101, v0
	v_sub_f32_e32 v0, v88, v68
	v_pk_add_f32 v[84:85], v[66:67], v[66:67] op_sel_hi:[0,1]
	v_exp_f32_e32 v102, v0
	v_sub_f32_e32 v0, v104, v68
	v_exp_f32_e32 v84, v0
	v_add_f32_e32 v103, v99, v101
	v_sub_f32_e32 v0, v89, v68
	v_cvt_pk_bf16_f32 v163, v114, v83
	v_pk_add_f32 v[66:67], v[102:103], v[84:85]
	v_exp_f32_e32 v85, v0
	v_sub_f32_e32 v0, v105, v68
	v_exp_f32_e32 v103, v0
	v_sub_f32_e32 v0, v90, v68
	v_pk_add_f32 v[86:87], v[66:67], v[66:67] op_sel_hi:[0,1]
	v_exp_f32_e32 v104, v0
	v_sub_f32_e32 v0, v106, v68
	v_exp_f32_e32 v86, v0
	v_add_f32_e32 v105, v85, v103
	v_sub_f32_e32 v0, v91, v68
	v_cvt_pk_bf16_f32 v164, v100, v99
	v_pk_add_f32 v[66:67], v[104:105], v[86:87]
	v_exp_f32_e32 v87, v0
	v_sub_f32_e32 v0, v107, v68
	v_exp_f32_e32 v105, v0
	v_sub_f32_e32 v0, v92, v68
	v_pk_add_f32 v[88:89], v[66:67], v[66:67] op_sel_hi:[0,1]
	v_exp_f32_e32 v90, v0
	v_sub_f32_e32 v0, v108, v68
	v_exp_f32_e32 v88, v0
	v_sub_f32_e32 v0, v97, v68
	v_exp_f32_e32 v97, v0
	v_add_f32_e32 v91, v87, v105
	v_sub_f32_e32 v0, v93, v68
	v_pk_add_f32 v[66:67], v[90:91], v[88:89]
	v_exp_f32_e32 v89, v0
	v_sub_f32_e32 v0, v109, v68
	v_exp_f32_e32 v91, v0
	v_sub_f32_e32 v0, v94, v68
	v_pk_add_f32 v[106:107], v[66:67], v[66:67] op_sel_hi:[0,1]
	v_exp_f32_e32 v92, v0
	v_sub_f32_e32 v0, v110, v68
	v_exp_f32_e32 v106, v0
	v_sub_f32_e32 v0, v113, v68
	v_exp_f32_e32 v110, v0
	v_add_f32_e32 v93, v89, v91
	v_sub_f32_e32 v0, v95, v68
	v_pk_add_f32 v[66:67], v[92:93], v[106:107]
	v_exp_f32_e32 v93, v0
	v_sub_f32_e32 v0, v111, v68
	v_exp_f32_e32 v107, v0
	v_sub_f32_e32 v0, v96, v68
	v_pk_add_f32 v[108:109], v[66:67], v[66:67] op_sel_hi:[0,1]
	v_exp_f32_e32 v94, v0
	v_sub_f32_e32 v0, v112, v68
	v_exp_f32_e32 v108, v0
	v_add_f32_e32 v95, v93, v107
	v_exp_f32_e64 v0, -v68
	v_add_f32_e32 v212, v97, v110
	v_pk_add_f32 v[66:67], v[94:95], v[108:109]
	v_cvt_pk_bf16_f32 v165, v102, v85
	v_pk_add_f32 v[66:67], v[66:67], v[66:67] op_sel:[0,1] op_sel_hi:[1,0]
	v_pk_mul_f32 v[64:65], v[64:65], v[0:1] op_sel_hi:[1,0]
	v_mov_b32_e32 v67, v68
	v_pk_add_f32 v[212:213], v[212:213], v[66:67]
	v_pk_mul_f32 v[62:63], v[62:63], v[0:1] op_sel_hi:[1,0]
	v_xor_b32_e32 v66, 0x80000000, v213
	v_mov_b32_e32 v67, v66
	v_mov_b32_e32 v68, v66
	v_mov_b32_e32 v69, v66
	v_mov_b32_e32 v70, v66
	v_mov_b32_e32 v71, v66
	v_mov_b32_e32 v72, v66
	v_mov_b32_e32 v73, v66
	v_mov_b32_e32 v74, v66
	v_mov_b32_e32 v75, v66
	v_mov_b32_e32 v76, v66
	v_mov_b32_e32 v77, v66
	v_mov_b32_e32 v78, v66
	v_mov_b32_e32 v79, v66
	v_mov_b32_e32 v80, v66
	v_mov_b32_e32 v81, v66
	v_pk_mul_f32 v[60:61], v[60:61], v[0:1] op_sel_hi:[1,0]
	v_pk_mul_f32 v[58:59], v[58:59], v[0:1] op_sel_hi:[1,0]
	v_pk_mul_f32 v[56:57], v[56:57], v[0:1] op_sel_hi:[1,0]
	v_pk_mul_f32 v[54:55], v[54:55], v[0:1] op_sel_hi:[1,0]
	v_pk_mul_f32 v[52:53], v[52:53], v[0:1] op_sel_hi:[1,0]
	v_pk_mul_f32 v[50:51], v[50:51], v[0:1] op_sel_hi:[1,0]
	v_pk_mul_f32 v[48:49], v[48:49], v[0:1] op_sel_hi:[1,0]
	v_pk_mul_f32 v[46:47], v[46:47], v[0:1] op_sel_hi:[1,0]
	v_pk_mul_f32 v[44:45], v[44:45], v[0:1] op_sel_hi:[1,0]
	v_pk_mul_f32 v[42:43], v[42:43], v[0:1] op_sel_hi:[1,0]
	v_pk_mul_f32 v[40:41], v[40:41], v[0:1] op_sel_hi:[1,0]
	v_pk_mul_f32 v[38:39], v[38:39], v[0:1] op_sel_hi:[1,0]
	v_pk_mul_f32 v[36:37], v[36:37], v[0:1] op_sel_hi:[1,0]
	v_pk_mul_f32 v[34:35], v[34:35], v[0:1] op_sel_hi:[1,0]
	v_pk_mul_f32 v[32:33], v[32:33], v[0:1] op_sel_hi:[1,0]
	v_pk_mul_f32 v[30:31], v[30:31], v[0:1] op_sel_hi:[1,0]
	v_pk_mul_f32 v[28:29], v[28:29], v[0:1] op_sel_hi:[1,0]
	v_pk_mul_f32 v[26:27], v[26:27], v[0:1] op_sel_hi:[1,0]
	v_pk_mul_f32 v[24:25], v[24:25], v[0:1] op_sel_hi:[1,0]
	v_pk_mul_f32 v[22:23], v[22:23], v[0:1] op_sel_hi:[1,0]
	v_pk_mul_f32 v[20:21], v[20:21], v[0:1] op_sel_hi:[1,0]
	v_pk_mul_f32 v[18:19], v[18:19], v[0:1] op_sel_hi:[1,0]
	v_pk_mul_f32 v[16:17], v[16:17], v[0:1] op_sel_hi:[1,0]
	v_pk_mul_f32 v[14:15], v[14:15], v[0:1] op_sel_hi:[1,0]
	v_pk_mul_f32 v[12:13], v[12:13], v[0:1] op_sel_hi:[1,0]
	v_pk_mul_f32 v[10:11], v[10:11], v[0:1] op_sel_hi:[1,0]
	v_pk_mul_f32 v[8:9], v[8:9], v[0:1] op_sel_hi:[1,0]
	v_pk_mul_f32 v[6:7], v[6:7], v[0:1] op_sel_hi:[1,0]
	v_pk_mul_f32 v[4:5], v[4:5], v[0:1] op_sel_hi:[1,0]
	v_pk_mul_f32 v[2:3], v[2:3], v[0:1] op_sel_hi:[1,0]
	v_mul_f32_e32 v243, v243, v0
	v_cvt_pk_bf16_f32 v170, v104, v87
	v_cvt_pk_bf16_f32 v171, v90, v89
	v_cvt_pk_bf16_f32 v172, v92, v93
	v_cvt_pk_bf16_f32 v173, v94, v97
	v_cvt_pk_bf16_f32 v178, v117, v119
	v_cvt_pk_bf16_f32 v179, v82, v115
	v_cvt_pk_bf16_f32 v180, v98, v101
	v_cvt_pk_bf16_f32 v181, v84, v103
	v_cvt_pk_bf16_f32 v186, v86, v105
	v_cvt_pk_bf16_f32 v187, v88, v91
	v_cvt_pk_bf16_f32 v188, v106, v107
	v_cvt_pk_bf16_f32 v189, v108, v110
